# lever4 on the pool mixer: one static s_setprio 1 for waves 4-7 for the whole phase so the two waves of a SIMD alternate load-wait and compute
# speedup vs baseline: 1.0038x; 1.0027x over previous
.LBB0_107:
	s_and_b64 vcc, exec, s[2:3]
	s_cbranch_vccz .LBB0_364
	v_readfirstlane_b32 s2, v210
	s_bitcmp1_b32 s2, 8
	s_cbranch_scc0 .Lpp_skip
	s_setprio 1
.Lpp_skip:
	v_readlane_b32 s2, v252, 30
	v_readlane_b32 s3, v252, 31
	s_lshl_b32 s2, s2, 10
	s_ashr_i32 s3, s2, 31
	v_readlane_b32 s6, v252, 24
	s_load_dwordx2 s[4:5], s[0:1], 0x60
	v_readlane_b32 s7, v252, 25
	s_add_u32 s6, s6, 0x13200000
	s_addc_u32 s7, s7, 0
	s_waitcnt lgkmcnt(0)
	s_add_u32 s8, s14, 0x1b300000
	s_addc_u32 s9, s15, 0
	s_lshl_b64 s[2:3], s[2:3], 2
	s_add_u32 s2, s4, s2
	s_load_dwordx2 s[16:17], s[0:1], 0x98
	s_waitcnt vmcnt(0)
	v_mov_b32 v155, v210
	s_addc_u32 s3, s5, s3
	v_readfirstlane_b32 s4, v155
	v_lshlrev_b32_e32 v0, 3, v155
	s_bfe_u32 s26, s4, 0x20006
	v_and_b32_e32 v0, 0xf8, v0
	v_lshl_or_b32 v9, s26, 8, v0
	v_lshlrev_b32_e32 v4, 2, v9
	global_load_dwordx4 v[0:3], v4, s[2:3] offset:16
	s_nop 0
	global_load_dwordx4 v[4:7], v4, s[2:3]
	s_ashr_i32 s4, s4, 7
	v_lshrrev_b32_e32 v8, 5, v155
	v_bfi_b32 v8, -2, s4, v8
	s_cmpk_gt_i32 s80, 0x7ff
	v_lshlrev_b32_e32 v153, 3, v8
	v_lshlrev_b32_e32 v96, 1, v9
	s_cbranch_scc1 .LBB0_238
	v_lshlrev_b32_e32 v161, 3, v8
	v_lshl_add_u64 v[134:135], s[12:13], 0, v[96:97]
	v_lshl_add_u64 v[136:137], s[6:7], 0, v[96:97]
	v_lshl_add_u64 v[138:139], s[8:9], 0, v[96:97]
	s_sub_i32 s5, 0x7ff, s80
	s_mov_b32 s18, s80
	s_branch .LBB0_112

.LBB0_365:
.LBB0_366:
	s_setprio 0
	s_andn2_b64 vcc, exec, s[2:3]
	s_cbranch_vccnz .LBB0_39
